# scan loader issue code: 64-bit per-lane address arithmetic replaced by 32-bit offsets against scalar base registers
# speedup vs baseline: 1.0038x; 1.0038x over previous
; __device__ __forceinline__ void scan_issue(const ScanPtrs& Q, int J, int ci, int ltid, LStage& L, int toff) {
;     ...
;         const int tok = jb.tok0 + tt; const int tseq = jb.is_s ? tt : ci * SC_CH + tt;
;         const int gc = jb.h * 64 + c;
;         const bf16_t* zr = Q.z + (size_t)tok * DIN + gc;
;         L.r = *(const u32x2*)zr; L.k = *(const u32x2*)(zr + 512); L.v = *(const u32x2*)(zr + 1024);
;         if (tseq > 0) { L.rp = *(const u32x2*)(zr - DIN); L.kp = *(const u32x2*)(zr - DIN + 512); L.vp = *(const u32x2*)(zr - DIN + 1024); }
;         else if (jb.is_s) { const float* sp = Q.st_shift + (size_t)jb.seq * DSH + gc; L.fr = *(const f32x4*)sp; L.fk = *(const f32x4*)(sp + 512); L.fv = *(const f32x4*)(sp + 1024); }
.LBB0_505:
	v_add_u32_e32 v20, v18, v96
	v_lshlrev_b32_e32 v18, 4, v1
	v_and_or_b32 v28, v18, s79, v97
	v_lshlrev_b32_e32 v18, 1, v28
	v_mad_u32_u24 v26, v20, s80, v18
	global_load_dwordx2 v[62:63], v26, s[24:25]
	global_load_dwordx2 v[70:71], v26, s[24:25] offset:1024
	global_load_dwordx2 v[72:73], v26, s[24:25] offset:2048
	v_lshlrev_b32_e32 v29, 5, v0
	v_cndmask_b32_e64 v29, v29, 0, vcc
	v_cmp_le_i32_e64 s[18:19], v29, v98
	s_and_saveexec_b64 s[6:7], s[18:19]
	s_xor_b64 s[18:19], exec, s[6:7]
	s_cbranch_execz .LBB0_509
	s_and_saveexec_b64 s[72:73], vcc
	s_cbranch_execz .LBB0_508
	s_waitcnt vmcnt(7)
	v_mov_b64_e32 v[6:7], s[28:29]
	v_mad_i64_i32 v[6:7], s[6:7], v21, s81, v[6:7]
	v_lshlrev_b32_e32 v8, 2, v28
	v_mov_b32_e32 v9, v19
	s_waitcnt vmcnt(5)
	v_lshl_add_u64 v[14:15], v[6:7], 0, v[8:9]
	global_load_dwordx4 v[6:9], v[14:15], off
	global_load_dwordx4 v[10:13], v[14:15], off offset:2048
	v_add_co_u32_e32 v14, vcc, 0x1000, v14
	s_nop 1
	v_addc_co_u32_e32 v15, vcc, 0, v15, vcc
	global_load_dwordx4 v[14:17], v[14:15], off

; __device__ __forceinline__ void scan_issue(const ScanPtrs& Q, int J, int ci, int ltid, LStage& L, int toff) {
;     ...
;         if (tseq > 0) { L.rp = *(const u32x2*)(zr - DIN); L.kp = *(const u32x2*)(zr - DIN + 512); L.vp = *(const u32x2*)(zr - DIN + 1024); }
;         else if (jb.is_s) { const float* sp = Q.st_shift + (size_t)jb.seq * DSH + gc; L.fr = *(const f32x4*)sp; L.fk = *(const f32x4*)(sp + 512); L.fv = *(const f32x4*)(sp + 1024); }
;         L.sw = *(const u32x2*)(Q.sw + (size_t)tok * 512 + gc); L.sa = *(const u32x2*)(Q.sa + (size_t)tok * 512 + gc);
.LBB0_509:
	s_andn2_saveexec_b64 s[18:19], s[18:19]
	s_cbranch_execz .LBB0_511
	v_add_u32_e32 v28, 0xffffde00, v26
	global_load_dwordx2 v[64:65], v28, s[24:25]
	global_load_dwordx2 v[74:75], v28, s[24:25] offset:1024
	global_load_dwordx2 v[76:77], v28, s[24:25] offset:2048
.LBB0_511:
	s_or_b64 exec, exec, s[18:19]
	v_lshl_add_u32 v26, v20, 10, v18
	global_load_dwordx2 v[82:83], v26, s[54:55]
	global_load_dwordx2 v[84:85], v26, s[26:27]
	s_or_b64 exec, exec, s[22:23]
	v_mov_b32_e32 v18, 1
	s_and_saveexec_b64 s[18:19], s[16:17]
	s_cbranch_execz .LBB0_520
	s_branch .LBB0_515

; __device__ __forceinline__ void scan_issue(const ScanPtrs& Q, int J, int ci, int ltid, LStage& L, int toff) {
;     ...
;     if (tt < jb.nsteps) {
;         const int tok = jb.tok0 + tt; const int tseq = jb.is_s ? tt : ci * SC_CH + tt;
;         const int gc = jb.h * 64 + c;
;         const bf16_t* zr = Q.z + (size_t)tok * DIN + gc;
;         L.r = *(const u32x2*)zr; L.k = *(const u32x2*)(zr + 512); L.v = *(const u32x2*)(zr + 1024);
;         if (tseq > 0) { L.rp = *(const u32x2*)(zr - DIN); L.kp = *(const u32x2*)(zr - DIN + 512); L.vp = *(const u32x2*)(zr - DIN + 1024); }
;         else if (jb.is_s) { const float* sp = Q.st_shift + (size_t)jb.seq * DSH + gc; L.fr = *(const f32x4*)sp; L.fk = *(const f32x4*)(sp + 512); L.fv = *(const f32x4*)(sp + 1024); }
;         L.sw = *(const u32x2*)(Q.sw + (size_t)tok * 512 + gc); L.sa = *(const u32x2*)(Q.sa + (size_t)tok * 512 + gc);
.LBB0_515:
	s_and_saveexec_b64 s[16:17], s[14:15]
	s_cbranch_execz .LBB0_519
	v_lshlrev_b32_e32 v18, 6, v1
	v_and_b32_e32 v18, 0xfffff800, v18
	v_lshlrev_b32_e32 v21, 5, v0
	v_add_u32_e32 v18, v18, v21
	v_or_b32_e32 v20, v18, v103
	v_lshlrev_b32_e32 v18, 4, v1
	v_and_or_b32 v18, v18, s79, v97
	v_lshlrev_b32_e32 v18, 1, v18
	v_mad_u32_u24 v26, v20, s80, v18
	global_load_dwordx2 v[56:57], v26, s[24:25]
	global_load_dwordx2 v[60:61], v26, s[24:25] offset:1024
	global_load_dwordx2 v[68:69], v26, s[24:25] offset:2048
	v_cmp_gt_i32_e32 vcc, v21, v104
	s_and_saveexec_b64 s[22:23], vcc
	s_cbranch_execz .LBB0_518
	v_add_u32_e32 v28, 0xffffde00, v26
	global_load_dwordx2 v[54:55], v28, s[24:25]
	global_load_dwordx2 v[58:59], v28, s[24:25] offset:1024
	global_load_dwordx2 v[66:67], v28, s[24:25] offset:2048
.LBB0_518:
	s_or_b64 exec, exec, s[22:23]
	v_lshl_add_u32 v26, v20, 10, v18
	global_load_dwordx2 v[78:79], v26, s[54:55]
	global_load_dwordx2 v[80:81], v26, s[26:27]

; __device__ __forceinline__ void scan_issue(const ScanPtrs& Q, int J, int ci, int ltid, LStage& L, int toff) {
;     ...
;         const int tok = jb.tok0 + tt; const int tseq = jb.is_s ? tt : ci * SC_CH + tt;
;         const int gc = jb.h * 64 + c;
;         const bf16_t* zr = Q.z + (size_t)tok * DIN + gc;
;         L.r = *(const u32x2*)zr; L.k = *(const u32x2*)(zr + 512); L.v = *(const u32x2*)(zr + 1024);
;         if (tseq > 0) { L.rp = *(const u32x2*)(zr - DIN); L.kp = *(const u32x2*)(zr - DIN + 512); L.vp = *(const u32x2*)(zr - DIN + 1024); }
;         else if (jb.is_s) { const float* sp = Q.st_shift + (size_t)jb.seq * DSH + gc; L.fr = *(const f32x4*)sp; L.fk = *(const f32x4*)(sp + 512); L.fv = *(const f32x4*)(sp + 1024); }
.LBB0_1646:
	v_add_u32_e32 v20, v18, v96
	v_lshlrev_b32_e32 v18, 4, v1
	v_and_or_b32 v28, v18, s80, v97
	v_lshlrev_b32_e32 v18, 1, v28
	v_mad_u32_u24 v26, v20, s81, v18
	global_load_dwordx2 v[62:63], v26, s[22:23]
	global_load_dwordx2 v[70:71], v26, s[22:23] offset:1024
	global_load_dwordx2 v[72:73], v26, s[22:23] offset:2048
	v_lshlrev_b32_e32 v29, 5, v0
	v_cndmask_b32_e64 v29, v29, 0, vcc
	v_cmp_le_i32_e64 s[16:17], v29, v98
	s_and_saveexec_b64 s[6:7], s[16:17]
	s_xor_b64 s[16:17], exec, s[6:7]
	s_cbranch_execz .LBB0_1650
	s_and_saveexec_b64 s[70:71], vcc
	s_cbranch_execz .LBB0_1649
	s_waitcnt vmcnt(7)
	v_mov_b64_e32 v[6:7], s[56:57]
	v_mad_i64_i32 v[6:7], s[6:7], v21, s82, v[6:7]
	v_lshlrev_b32_e32 v8, 2, v28
	v_mov_b32_e32 v9, v19
	s_waitcnt vmcnt(5)
	v_lshl_add_u64 v[14:15], v[6:7], 0, v[8:9]
	global_load_dwordx4 v[6:9], v[14:15], off
	global_load_dwordx4 v[10:13], v[14:15], off offset:2048
	v_add_co_u32_e32 v14, vcc, 0x1000, v14
	s_nop 1
	v_addc_co_u32_e32 v15, vcc, 0, v15, vcc
	global_load_dwordx4 v[14:17], v[14:15], off

; __device__ __forceinline__ void scan_issue(const ScanPtrs& Q, int J, int ci, int ltid, LStage& L, int toff) {
;     ...
;         if (tseq > 0) { L.rp = *(const u32x2*)(zr - DIN); L.kp = *(const u32x2*)(zr - DIN + 512); L.vp = *(const u32x2*)(zr - DIN + 1024); }
;         else if (jb.is_s) { const float* sp = Q.st_shift + (size_t)jb.seq * DSH + gc; L.fr = *(const f32x4*)sp; L.fk = *(const f32x4*)(sp + 512); L.fv = *(const f32x4*)(sp + 1024); }
;         L.sw = *(const u32x2*)(Q.sw + (size_t)tok * 512 + gc); L.sa = *(const u32x2*)(Q.sa + (size_t)tok * 512 + gc);
.LBB0_1650:
	s_andn2_saveexec_b64 s[16:17], s[16:17]
	s_cbranch_execz .LBB0_1652
	v_add_u32_e32 v28, 0xffffde00, v26
	global_load_dwordx2 v[64:65], v28, s[22:23]
	global_load_dwordx2 v[74:75], v28, s[22:23] offset:1024
	global_load_dwordx2 v[76:77], v28, s[22:23] offset:2048
.LBB0_1652:
	s_or_b64 exec, exec, s[16:17]
	v_lshl_add_u32 v26, v20, 10, v18
	global_load_dwordx2 v[82:83], v26, s[54:55]
	global_load_dwordx2 v[84:85], v26, s[24:25]
	s_or_b64 exec, exec, s[20:21]
	v_mov_b32_e32 v18, 1
	s_and_saveexec_b64 s[16:17], s[14:15]
	s_cbranch_execz .LBB0_1661
	s_branch .LBB0_1656

; __device__ __forceinline__ void scan_issue(const ScanPtrs& Q, int J, int ci, int ltid, LStage& L, int toff) {
;     ...
;     if (tt < jb.nsteps) {
;         const int tok = jb.tok0 + tt; const int tseq = jb.is_s ? tt : ci * SC_CH + tt;
;         const int gc = jb.h * 64 + c;
;         const bf16_t* zr = Q.z + (size_t)tok * DIN + gc;
;         L.r = *(const u32x2*)zr; L.k = *(const u32x2*)(zr + 512); L.v = *(const u32x2*)(zr + 1024);
;         if (tseq > 0) { L.rp = *(const u32x2*)(zr - DIN); L.kp = *(const u32x2*)(zr - DIN + 512); L.vp = *(const u32x2*)(zr - DIN + 1024); }
;         else if (jb.is_s) { const float* sp = Q.st_shift + (size_t)jb.seq * DSH + gc; L.fr = *(const f32x4*)sp; L.fk = *(const f32x4*)(sp + 512); L.fv = *(const f32x4*)(sp + 1024); }
;         L.sw = *(const u32x2*)(Q.sw + (size_t)tok * 512 + gc); L.sa = *(const u32x2*)(Q.sa + (size_t)tok * 512 + gc);
.LBB0_1656:
	s_and_saveexec_b64 s[14:15], s[12:13]
	s_cbranch_execz .LBB0_1660
	v_lshlrev_b32_e32 v18, 6, v1
	v_and_b32_e32 v18, 0xfffff800, v18
	v_lshlrev_b32_e32 v21, 5, v0
	v_add_u32_e32 v18, v18, v21
	v_or_b32_e32 v20, v18, v103
	v_lshlrev_b32_e32 v18, 4, v1
	v_and_or_b32 v18, v18, s80, v97
	v_lshlrev_b32_e32 v18, 1, v18
	v_mad_u32_u24 v26, v20, s81, v18
	global_load_dwordx2 v[56:57], v26, s[22:23]
	global_load_dwordx2 v[60:61], v26, s[22:23] offset:1024
	global_load_dwordx2 v[68:69], v26, s[22:23] offset:2048
	v_cmp_gt_i32_e32 vcc, v21, v104
	s_and_saveexec_b64 s[20:21], vcc
	s_cbranch_execz .LBB0_1659
	v_add_u32_e32 v28, 0xffffde00, v26
	global_load_dwordx2 v[54:55], v28, s[22:23]
	global_load_dwordx2 v[58:59], v28, s[22:23] offset:1024
	global_load_dwordx2 v[66:67], v28, s[22:23] offset:2048
.LBB0_1659:
	s_or_b64 exec, exec, s[20:21]
	v_lshl_add_u32 v26, v20, 10, v18
	global_load_dwordx2 v[78:79], v26, s[54:55]
	global_load_dwordx2 v[80:81], v26, s[24:25]
